# attention tile loop: next tile's K/V^T LDS image written inside the body (second softmax block) instead of after the body in front of the barrier
# speedup vs baseline: 1.0100x; 1.0100x over previous
; __device__ __forceinline__ void attn_unit(const TI ti, CArgs& a, int b, int hd, int qrow0, int st_lo, int st_hi, float mfix, float lam, float lam_init, const float* subg, unsigned char* ldsg) {
;     ...
;     ATT_LOAD(st_lo); ATT_STORE(0);
;     __syncthreads();
;     for (int st = st_lo; st < st_hi; ++st) {
;         const int bi = (st - st_lo) & 1;
;         if (st + 1 < st_hi) ATT_LOAD(st + 1);
;     ...
;         if (st + 1 < st_hi) ATT_STORE(bi ^ 1);
;         __syncthreads();
.LBB0_351:
	s_or_b64 exec, exec, s[4:5]
	s_add_i32 s17, s17, 1
	s_setprio 0
	s_add_i32 s37, s37, 64
	s_add_i32 s39, s39, 64
	s_waitcnt lgkmcnt(0)
	s_cmp_eq_u32 s17, 35
	s_cbranch_scc1 .Lattn_last
	s_cmp_lt_u32 s17, 31
	s_cselect_b32 s4, s39, s37
	s_ashr_i32 s5, s4, 31
	s_lshl_b64 s[4:5], s[4:5], 11
	s_add_u32 s33, s27, s4
	s_addc_u32 s36, s34, s5
	v_mov_b32_e32 v82, s33
	v_mov_b32_e32 v83, s36
	s_add_u32 s4, s18, s4
	s_addc_u32 s5, s35, s5
	v_lshl_add_u64 v[82:83], v[140:141], 1, v[82:83]
	v_mov_b32_e32 v84, s4
	v_mov_b32_e32 v85, s5
	v_add_co_u32_e32 v86, vcc, s79, v82
	s_nop 0
	v_addc_co_u32_e32 v87, vcc, 0, v83, vcc
	global_load_dwordx4 v[122:125], v[82:83], off
	global_load_dwordx4 v[126:129], v[86:87], off
	v_lshl_add_u64 v[82:83], v[142:143], 1, v[84:85]
	global_load_dwordx4 v[118:121], v[82:83], off
	global_load_dwordx4 v[114:117], v[82:83], off offset:16
	s_and_b32 s48, s17, 1
	s_mul_i32 s4, s48, 0x8c00
	s_add_i32 s4, s4, 0
	v_add_u32_e32 v82, s4, v160
	v_add_u32_e32 v151, v82, v161
	v_add3_u32 v150, s4, v144, v162
	s_xor_b32 s5, s48, 1
	s_mul_i32 s5, s5, 0x8c00
	v_add_u32_e32 v250, s5, v147
	v_add_u32_e32 v251, v250, v156
	v_add_u32_e32 v250, v250, v155
	v_add3_u32 v252, s5, v157, v158
	s_barrier
	s_branch .Lattn_body

; #define LAS __attribute__((address_space(3)))
; #define ATT_QK(SX, sub) do { __builtin_amdgcn_s_setprio(1); _Pragma("unroll") for (int ks = 0; ks < 4; ++ks) { \
;             const bf16x8 kf = *(LAS const bf16x8*)(Bb + KOFF + ((sub) * 32 + r) * 272 + (c * 64 + 16 * ks + 8 * h) * 2); SX = MFMA32(kf, qf[ks], SX); } __builtin_amdgcn_s_setprio(0); } while (0)
; #define ATT_SOFT(SX, P0, P1) do { float p[16]; _Pragma("unroll") for (int i = 0; i < 16; ++i) { p[i] = __builtin_amdgcn_exp2f(SX[i]); lsum += p[i]; } \
;             P0 = pk8f(p[0], p[1], p[2], p[3], p[4], p[5], p[6], p[7]); P1 = pk8f(p[8], p[9], p[10], p[11], p[12], p[13], p[14], p[15]); } while (0)
; #define ATT_PV(sub, P0, P1) do { __builtin_amdgcn_s_setprio(1); _Pragma("unroll") for (int et = 0; et < 4; ++et) { _Pragma("unroll") for (int s = 0; s < 2; ++s) { \
;             const bf16x8 vf = *(LAS const bf16x8*)(Bb + VOFF + (et * 32 + r) * 144 + ((sub) * 32 + 16 * s + 8 * h) * 2); O[et] = MFMA32(vf, s ? P1 : P0, O[et]); } } __builtin_amdgcn_s_setprio(0); } while (0)
; __device__ __forceinline__ void attn_unit(const TI ti, CArgs& a, int b, int hd, int qrow0, int st_lo, int st_hi, float mfix, float lam, float lam_init, const float* subg, unsigned char* ldsg) {
;     ...
;         const int bi = (st - st_lo) & 1;
;         if (st + 1 < st_hi) ATT_LOAD(st + 1);
;         LAS const unsigned char* Bb = L + bi * BUFB;
;         f32x16 Sx0, Sx1; bf16x8 pa0, pa1, pc0, pc1;
; #pragma unroll
;         for (int i = 0; i < 16; ++i) { Sx0[i] = -mfix; Sx1[i] = -mfix; }
;     ...
;         if (w < 4) {
;             ATT_QK(Sx0, 0); ATT_QK(Sx1, 1);
;             __builtin_amdgcn_sched_barrier(0);
;             ATT_SOFT(Sx0, pa0, pa1); ATT_PV(0, pa0, pa1);
;             ATT_SOFT(Sx1, pc0, pc1); ATT_PV(1, pc0, pc1);
.LBB0_352:
	s_cmp_lt_u32 s17, 31
	s_cselect_b32 s4, s39, s37
	s_ashr_i32 s5, s4, 31
	s_lshl_b64 s[4:5], s[4:5], 11
	s_add_u32 s33, s27, s4
	s_addc_u32 s36, s34, s5
	v_mov_b32_e32 v82, s33
	v_mov_b32_e32 v83, s36
	s_add_u32 s4, s18, s4
	s_addc_u32 s5, s35, s5
	v_lshl_add_u64 v[82:83], v[140:141], 1, v[82:83]
	v_mov_b32_e32 v84, s4
	v_mov_b32_e32 v85, s5
	v_add_co_u32_e32 v86, vcc, s79, v82
	s_nop 0
	v_addc_co_u32_e32 v87, vcc, 0, v83, vcc
	global_load_dwordx4 v[122:125], v[82:83], off
	global_load_dwordx4 v[126:129], v[86:87], off
	v_lshl_add_u64 v[82:83], v[142:143], 1, v[84:85]
	global_load_dwordx4 v[118:121], v[82:83], off
	global_load_dwordx4 v[114:117], v[82:83], off offset:16
	s_and_b32 s48, s17, 1
	s_mul_i32 s4, s48, 0x8c00
	s_add_i32 s4, s4, 0
	v_add_u32_e32 v82, s4, v160
	v_add_u32_e32 v151, v82, v161
	v_add3_u32 v150, s4, v144, v162
	s_xor_b32 s5, s48, 1
	s_mul_i32 s5, s5, 0x8c00
	v_add_u32_e32 v250, s5, v147
	v_add_u32_e32 v251, v250, v156
	v_add_u32_e32 v250, v250, v155
	v_add3_u32 v252, s5, v157, v158
.Lattn_body:
	s_setprio 1
	ds_read_b128 v[130:133], v151
	s_and_saveexec_b64 s[4:5], s[40:41]
	s_xor_b64 s[4:5], exec, s[4:5]
	s_cbranch_execz .LBB0_354
	ds_read_b128 v[182:185], v151 offset:32
	ds_read_b128 v[198:201], v151 offset:64
	ds_read_b128 v[202:205], v151 offset:96
	ds_read_b128 v[206:209], v151 offset:8704
	ds_read_b128 v[210:213], v151 offset:8736
	ds_read_b128 v[236:239], v151 offset:8768
	ds_read_b128 v[240:243], v151 offset:8800
	s_setprio 1
	s_waitcnt lgkmcnt(7)
	v_mfma_f32_32x32x16_bf16 v[82:97], v[130:133], v[110:113], v[2:17]
	s_waitcnt lgkmcnt(6)
	v_mfma_f32_32x32x16_bf16 v[82:97], v[182:185], v[106:109], v[82:97]
	s_waitcnt lgkmcnt(5)
	v_mfma_f32_32x32x16_bf16 v[82:97], v[198:201], v[102:105], v[82:97]
	s_waitcnt lgkmcnt(4)
	v_mfma_f32_32x32x16_bf16 v[82:97], v[202:205], v[98:101], v[82:97]
	ds_read_b128 v[130:133], v150 offset:17408
	ds_read_b128 v[182:185], v150 offset:17440
	ds_read_b128 v[198:201], v150 offset:22016
	ds_read_b128 v[202:205], v150 offset:22048
	s_waitcnt lgkmcnt(7)
	v_mfma_f32_32x32x16_bf16 v[220:235], v[206:209], v[110:113], v[2:17]
	s_waitcnt lgkmcnt(6)
	v_mfma_f32_32x32x16_bf16 v[220:235], v[210:213], v[106:109], v[220:235]
	s_waitcnt lgkmcnt(5)
	v_mfma_f32_32x32x16_bf16 v[220:235], v[236:239], v[102:105], v[220:235]
	s_waitcnt lgkmcnt(4)
	v_mfma_f32_32x32x16_bf16 v[220:235], v[240:243], v[98:101], v[220:235]
	ds_read_b128 v[206:209], v150 offset:26624
	ds_read_b128 v[210:213], v150 offset:26656
	ds_read_b128 v[236:239], v150 offset:31232
	ds_read_b128 v[240:243], v150 offset:31264
	s_setprio 0
	v_exp_f32_e32 v169, v82
	v_exp_f32_e32 v170, v83
	v_exp_f32_e32 v171, v84
	v_exp_f32_e32 v174, v85
	v_exp_f32_e32 v175, v86
	v_exp_f32_e32 v176, v87
	v_exp_f32_e32 v177, v88
	v_exp_f32_e32 v179, v89
	v_exp_f32_e32 v90, v90
	v_exp_f32_e32 v91, v91
	v_exp_f32_e32 v92, v92
	v_exp_f32_e32 v93, v93
	v_exp_f32_e32 v94, v94
	v_exp_f32_e32 v95, v95
	v_exp_f32_e32 v96, v96
	v_exp_f32_e32 v97, v97
	v_cvt_pk_bf16_f32 v82, v169, v170
	v_cvt_pk_bf16_f32 v83, v171, v174
	v_cvt_pk_bf16_f32 v84, v175, v176
	v_cvt_pk_bf16_f32 v85, v177, v179
	v_cvt_pk_bf16_f32 v86, v90, v91
	v_cvt_pk_bf16_f32 v87, v92, v93
	v_cvt_pk_bf16_f32 v88, v94, v95
	v_cvt_pk_bf16_f32 v89, v96, v97
	s_setprio 1
	s_waitcnt lgkmcnt(7)
	v_mfma_f32_32x32x16_bf16 v[18:33], v[130:133], v[82:85], v[18:33]
	v_add_f32_e32 v0, v169, v0
	v_add_f32_e32 v0, v170, v0
	s_waitcnt lgkmcnt(6)
	v_mfma_f32_32x32x16_bf16 v[18:33], v[182:185], v[86:89], v[18:33]
	v_add_f32_e32 v0, v171, v0
	v_add_f32_e32 v0, v174, v0
	ds_read_b128 v[130:133], v150 offset:17472
	ds_read_b128 v[182:185], v150 offset:17504
	s_waitcnt lgkmcnt(7)
	v_mfma_f32_32x32x16_bf16 v[34:49], v[198:201], v[82:85], v[34:49]
	v_add_f32_e32 v0, v175, v0
	v_add_f32_e32 v0, v176, v0
	s_waitcnt lgkmcnt(6)
	v_mfma_f32_32x32x16_bf16 v[34:49], v[202:205], v[86:89], v[34:49]
	v_add_f32_e32 v0, v177, v0
	v_add_f32_e32 v0, v179, v0
	ds_read_b128 v[198:201], v150 offset:22080
	ds_read_b128 v[202:205], v150 offset:22112
	s_waitcnt lgkmcnt(7)
	v_mfma_f32_32x32x16_bf16 v[66:81], v[206:209], v[82:85], v[66:81]
	v_add_f32_e32 v0, v90, v0
	v_add_f32_e32 v0, v91, v0
	s_waitcnt lgkmcnt(6)
	v_mfma_f32_32x32x16_bf16 v[66:81], v[210:213], v[86:89], v[66:81]
	v_add_f32_e32 v0, v92, v0
	v_add_f32_e32 v0, v93, v0
	ds_read_b128 v[206:209], v150 offset:26688
	ds_read_b128 v[210:213], v150 offset:26720
	s_waitcnt lgkmcnt(7)
	v_mfma_f32_32x32x16_bf16 v[50:65], v[236:239], v[82:85], v[50:65]
	v_add_f32_e32 v0, v94, v0
	v_add_f32_e32 v0, v95, v0
	s_waitcnt lgkmcnt(6)
	v_mfma_f32_32x32x16_bf16 v[50:65], v[240:243], v[86:89], v[50:65]
	v_add_f32_e32 v0, v96, v0
	v_add_f32_e32 v0, v97, v0
	ds_read_b128 v[236:239], v150 offset:31296
	ds_read_b128 v[240:243], v150 offset:31328
	s_setprio 0
	s_waitcnt vmcnt(0)
	ds_write_b128 v250, v[122:125]
	ds_write_b128 v251, v[126:129]
	ds_write_b16 v252, v118 offset:17408
	ds_write_b16_d16_hi v252, v118 offset:17552
	ds_write_b16 v252, v114 offset:18560
	ds_write_b16_d16_hi v252, v114 offset:18704
	ds_write_b16 v252, v119 offset:17696
	ds_write_b16_d16_hi v252, v119 offset:17840
	ds_write_b16 v252, v115 offset:18848
	ds_write_b16_d16_hi v252, v115 offset:18992
	ds_write_b16 v252, v120 offset:17984
	ds_write_b16_d16_hi v252, v120 offset:18128
	ds_write_b16 v252, v116 offset:19136
	ds_write_b16_d16_hi v252, v116 offset:19280
	ds_write_b16 v252, v121 offset:18272
	ds_write_b16_d16_hi v252, v121 offset:18416
	ds_write_b16 v252, v117 offset:19424
	ds_write_b16_d16_hi v252, v117 offset:19568
	v_exp_f32_e32 v181, v220
	v_exp_f32_e32 v197, v221
	v_exp_f32_e32 v214, v222
	v_exp_f32_e32 v244, v223
	v_exp_f32_e32 v245, v224
	v_exp_f32_e32 v246, v225
	v_exp_f32_e32 v247, v226
	v_exp_f32_e32 v248, v227
	v_exp_f32_e32 v228, v228
	v_exp_f32_e32 v229, v229
	v_exp_f32_e32 v230, v230
	v_exp_f32_e32 v231, v231
	v_exp_f32_e32 v232, v232
	v_exp_f32_e32 v233, v233
	v_exp_f32_e32 v234, v234
	v_exp_f32_e32 v235, v235
	v_cvt_pk_bf16_f32 v220, v181, v197
	v_cvt_pk_bf16_f32 v221, v214, v244
	v_cvt_pk_bf16_f32 v222, v245, v246
	v_cvt_pk_bf16_f32 v223, v247, v248
	v_cvt_pk_bf16_f32 v224, v228, v229
	v_cvt_pk_bf16_f32 v225, v230, v231
	v_cvt_pk_bf16_f32 v226, v232, v233
	v_cvt_pk_bf16_f32 v227, v234, v235
	s_waitcnt lgkmcnt(0)
; #define ATT_SOFT(SX, P0, P1) do { float p[16]; _Pragma("unroll") for (int i = 0; i < 16; ++i) { p[i] = __builtin_amdgcn_exp2f(SX[i]); lsum += p[i]; } \
;             P0 = pk8f(p[0], p[1], p[2], p[3], p[4], p[5], p[6], p[7]); P1 = pk8f(p[8], p[9], p[10], p[11], p[12], p[13], p[14], p[15]); } while (0)
; #define ATT_PV(sub, P0, P1) do { __builtin_amdgcn_s_setprio(1); _Pragma("unroll") for (int et = 0; et < 4; ++et) { _Pragma("unroll") for (int s = 0; s < 2; ++s) { \
;             const bf16x8 vf = *(LAS const bf16x8*)(Bb + VOFF + (et * 32 + r) * 144 + ((sub) * 32 + 16 * s + 8 * h) * 2); O[et] = MFMA32(vf, s ? P1 : P0, O[et]); } } __builtin_amdgcn_s_setprio(0); } while (0)
; __device__ __forceinline__ void attn_unit(const TI ti, CArgs& a, int b, int hd, int qrow0, int st_lo, int st_hi, float mfix, float lam, float lam_init, const float* subg, unsigned char* ldsg) {
;     ...
;             ATT_SOFT(Sx0, pa0, pa1); ATT_PV(0, pa0, pa1);
;             ATT_SOFT(Sx1, pc0, pc1); ATT_PV(1, pc0, pc1);
	s_setprio 1
	v_mfma_f32_32x32x16_bf16 v[18:33], v[130:133], v[220:223], v[18:33]
	v_add_f32_e32 v0, v181, v0
	v_add_f32_e32 v0, v197, v0
	v_mfma_f32_32x32x16_bf16 v[18:33], v[182:185], v[224:227], v[18:33]
	v_add_f32_e32 v0, v214, v0
	v_add_f32_e32 v0, v244, v0
	v_mfma_f32_32x32x16_bf16 v[34:49], v[198:201], v[220:223], v[34:49]
	v_add_f32_e32 v0, v245, v0
	v_add_f32_e32 v0, v246, v0
	v_mfma_f32_32x32x16_bf16 v[34:49], v[202:205], v[224:227], v[34:49]
	v_add_f32_e32 v0, v247, v0
	v_add_f32_e32 v0, v248, v0
	v_mfma_f32_32x32x16_bf16 v[66:81], v[206:209], v[220:223], v[66:81]
	v_add_f32_e32 v0, v228, v0
	v_add_f32_e32 v0, v229, v0
	v_mfma_f32_32x32x16_bf16 v[66:81], v[210:213], v[224:227], v[66:81]
	v_add_f32_e32 v0, v230, v0
	v_add_f32_e32 v0, v231, v0
	v_mfma_f32_32x32x16_bf16 v[50:65], v[236:239], v[220:223], v[50:65]
	v_add_f32_e32 v0, v232, v0
	v_add_f32_e32 v0, v233, v0
	v_mfma_f32_32x32x16_bf16 v[50:65], v[240:243], v[224:227], v[50:65]
	v_add_f32_e32 v0, v234, v0
	v_add_f32_e32 v0, v235, v0
; #define ATT_QK(SX, sub) do { __builtin_amdgcn_s_setprio(1); _Pragma("unroll") for (int ks = 0; ks < 4; ++ks) { \
;             const bf16x8 kf = *(LAS const bf16x8*)(Bb + KOFF + ((sub) * 32 + r) * 272 + (c * 64 + 16 * ks + 8 * h) * 2); SX = MFMA32(kf, qf[ks], SX); } __builtin_amdgcn_s_setprio(0); } while (0)
; #define ATT_SOFT(SX, P0, P1) do { float p[16]; _Pragma("unroll") for (int i = 0; i < 16; ++i) { p[i] = __builtin_amdgcn_exp2f(SX[i]); lsum += p[i]; } \
;             P0 = pk8f(p[0], p[1], p[2], p[3], p[4], p[5], p[6], p[7]); P1 = pk8f(p[8], p[9], p[10], p[11], p[12], p[13], p[14], p[15]); } while (0)
; #define ATT_PV(sub, P0, P1) do { __builtin_amdgcn_s_setprio(1); _Pragma("unroll") for (int et = 0; et < 4; ++et) { _Pragma("unroll") for (int s = 0; s < 2; ++s) { \
;             const bf16x8 vf = *(LAS const bf16x8*)(Bb + VOFF + (et * 32 + r) * 144 + ((sub) * 32 + 16 * s + 8 * h) * 2); O[et] = MFMA32(vf, s ? P1 : P0, O[et]); } } __builtin_amdgcn_s_setprio(0); } while (0)
; __device__ __forceinline__ void attn_unit(const TI ti, CArgs& a, int b, int hd, int qrow0, int st_lo, int st_hi, float mfix, float lam, float lam_init, const float* subg, unsigned char* ldsg) {
;     ...
;         } else {
;             ATT_QK(Sx0, 0);
;             __builtin_amdgcn_sched_barrier(0);
;             ATT_SOFT(Sx0, pa0, pa1);
;             __builtin_amdgcn_sched_barrier(0);
;             ATT_QK(Sx1, 1); ATT_PV(0, pa0, pa1);
;             __builtin_amdgcn_sched_barrier(0);
;             ATT_SOFT(Sx1, pc0, pc1); ATT_PV(1, pc0, pc1);
;         }
.LBB0_354:
	s_andn2_saveexec_b64 s[4:5], s[4:5]
	s_cbranch_execz .LBB0_351
	ds_read_b128 v[182:185], v151 offset:32
	ds_read_b128 v[198:201], v151 offset:64
	ds_read_b128 v[202:205], v151 offset:96
	ds_read_b128 v[206:209], v151 offset:8704
	ds_read_b128 v[210:213], v151 offset:8736
	ds_read_b128 v[236:239], v151 offset:8768
	ds_read_b128 v[240:243], v151 offset:8800
	s_setprio 1
	s_waitcnt lgkmcnt(7)
	v_mfma_f32_32x32x16_bf16 v[82:97], v[130:133], v[110:113], v[2:17]
	s_waitcnt lgkmcnt(6)
	v_mfma_f32_32x32x16_bf16 v[82:97], v[182:185], v[106:109], v[82:97]
	s_waitcnt lgkmcnt(5)
	v_mfma_f32_32x32x16_bf16 v[82:97], v[198:201], v[102:105], v[82:97]
	s_waitcnt lgkmcnt(4)
	v_mfma_f32_32x32x16_bf16 v[82:97], v[202:205], v[98:101], v[82:97]
	ds_read_b128 v[130:133], v150 offset:17408
	ds_read_b128 v[182:185], v150 offset:17440
	ds_read_b128 v[198:201], v150 offset:22016
	ds_read_b128 v[202:205], v150 offset:22048
	s_setprio 0
	s_nop 6
	v_exp_f32_e32 v169, v82
	v_exp_f32_e32 v170, v83
	v_exp_f32_e32 v171, v84
	v_exp_f32_e32 v174, v85
	v_exp_f32_e32 v175, v86
	v_exp_f32_e32 v176, v87
	v_exp_f32_e32 v177, v88
	v_exp_f32_e32 v179, v89
	v_exp_f32_e32 v90, v90
	v_exp_f32_e32 v91, v91
	v_exp_f32_e32 v92, v92
	v_exp_f32_e32 v93, v93
	v_exp_f32_e32 v94, v94
	v_exp_f32_e32 v95, v95
	v_exp_f32_e32 v96, v96
	v_exp_f32_e32 v97, v97
	v_cvt_pk_bf16_f32 v82, v169, v170
	v_cvt_pk_bf16_f32 v83, v171, v174
	v_cvt_pk_bf16_f32 v84, v175, v176
	v_cvt_pk_bf16_f32 v85, v177, v179
	v_cvt_pk_bf16_f32 v86, v90, v91
	v_cvt_pk_bf16_f32 v87, v92, v93
	v_cvt_pk_bf16_f32 v88, v94, v95
	v_cvt_pk_bf16_f32 v89, v96, v97
	s_setprio 1
	s_waitcnt lgkmcnt(7)
	v_mfma_f32_32x32x16_bf16 v[220:235], v[206:209], v[110:113], v[2:17]
	s_waitcnt lgkmcnt(6)
	v_mfma_f32_32x32x16_bf16 v[220:235], v[210:213], v[106:109], v[220:235]
	s_waitcnt lgkmcnt(5)
	v_mfma_f32_32x32x16_bf16 v[220:235], v[236:239], v[102:105], v[220:235]
	s_waitcnt lgkmcnt(4)
	v_mfma_f32_32x32x16_bf16 v[220:235], v[240:243], v[98:101], v[220:235]
	ds_read_b128 v[206:209], v150 offset:26624
	ds_read_b128 v[210:213], v150 offset:26656
	ds_read_b128 v[236:239], v150 offset:31232
	ds_read_b128 v[240:243], v150 offset:31264
	s_waitcnt lgkmcnt(7)
	v_mfma_f32_32x32x16_bf16 v[18:33], v[130:133], v[82:85], v[18:33]
	v_add_f32_e32 v0, v169, v0
	v_add_f32_e32 v0, v170, v0
	s_waitcnt lgkmcnt(6)
	v_mfma_f32_32x32x16_bf16 v[18:33], v[182:185], v[86:89], v[18:33]
	v_add_f32_e32 v0, v171, v0
	v_add_f32_e32 v0, v174, v0
	ds_read_b128 v[130:133], v150 offset:17472
	ds_read_b128 v[182:185], v150 offset:17504
	s_waitcnt lgkmcnt(7)
	v_mfma_f32_32x32x16_bf16 v[34:49], v[198:201], v[82:85], v[34:49]
	v_add_f32_e32 v0, v175, v0
	v_add_f32_e32 v0, v176, v0
	s_waitcnt lgkmcnt(6)
	v_mfma_f32_32x32x16_bf16 v[34:49], v[202:205], v[86:89], v[34:49]
	v_add_f32_e32 v0, v177, v0
	v_add_f32_e32 v0, v179, v0
	ds_read_b128 v[198:201], v150 offset:22080
	ds_read_b128 v[202:205], v150 offset:22112
	s_waitcnt lgkmcnt(7)
	v_mfma_f32_32x32x16_bf16 v[66:81], v[206:209], v[82:85], v[66:81]
	v_add_f32_e32 v0, v90, v0
	v_add_f32_e32 v0, v91, v0
	s_waitcnt lgkmcnt(6)
	v_mfma_f32_32x32x16_bf16 v[66:81], v[210:213], v[86:89], v[66:81]
	v_add_f32_e32 v0, v92, v0
	v_add_f32_e32 v0, v93, v0
	ds_read_b128 v[206:209], v150 offset:26688
	ds_read_b128 v[210:213], v150 offset:26720
	s_waitcnt lgkmcnt(7)
	v_mfma_f32_32x32x16_bf16 v[50:65], v[236:239], v[82:85], v[50:65]
	v_add_f32_e32 v0, v94, v0
	v_add_f32_e32 v0, v95, v0
	s_waitcnt lgkmcnt(6)
	v_mfma_f32_32x32x16_bf16 v[50:65], v[240:243], v[86:89], v[50:65]
	v_add_f32_e32 v0, v96, v0
	v_add_f32_e32 v0, v97, v0
	ds_read_b128 v[236:239], v150 offset:31296
	ds_read_b128 v[240:243], v150 offset:31328
	s_setprio 0
	s_waitcnt vmcnt(0)
	ds_write_b128 v250, v[122:125]
	ds_write_b128 v251, v[126:129]
	ds_write_b16 v252, v118 offset:17408
	ds_write_b16_d16_hi v252, v118 offset:17552
	ds_write_b16 v252, v114 offset:18560
	ds_write_b16_d16_hi v252, v114 offset:18704
	ds_write_b16 v252, v119 offset:17696
	ds_write_b16_d16_hi v252, v119 offset:17840
	ds_write_b16 v252, v115 offset:18848
	ds_write_b16_d16_hi v252, v115 offset:18992
	ds_write_b16 v252, v120 offset:17984
	ds_write_b16_d16_hi v252, v120 offset:18128
	ds_write_b16 v252, v116 offset:19136
	ds_write_b16_d16_hi v252, v116 offset:19280
	ds_write_b16 v252, v121 offset:18272
	ds_write_b16_d16_hi v252, v121 offset:18416
	ds_write_b16 v252, v117 offset:19424
	ds_write_b16_d16_hi v252, v117 offset:19568
	v_exp_f32_e32 v181, v220
	v_exp_f32_e32 v197, v221
	v_exp_f32_e32 v214, v222
	v_exp_f32_e32 v244, v223
	v_exp_f32_e32 v245, v224
	v_exp_f32_e32 v246, v225
	v_exp_f32_e32 v247, v226
	v_exp_f32_e32 v248, v227
	v_exp_f32_e32 v228, v228
	v_exp_f32_e32 v229, v229
	v_exp_f32_e32 v230, v230
	v_exp_f32_e32 v231, v231
	v_exp_f32_e32 v232, v232
	v_exp_f32_e32 v233, v233
	v_exp_f32_e32 v234, v234
	v_exp_f32_e32 v235, v235
	v_cvt_pk_bf16_f32 v220, v181, v197
	v_cvt_pk_bf16_f32 v221, v214, v244
	v_cvt_pk_bf16_f32 v222, v245, v246
	v_cvt_pk_bf16_f32 v223, v247, v248
	v_cvt_pk_bf16_f32 v224, v228, v229
	v_cvt_pk_bf16_f32 v225, v230, v231
	v_cvt_pk_bf16_f32 v226, v232, v233
	v_cvt_pk_bf16_f32 v227, v234, v235
	s_waitcnt lgkmcnt(0)
	s_setprio 1
	v_mfma_f32_32x32x16_bf16 v[18:33], v[130:133], v[220:223], v[18:33]
	v_add_f32_e32 v0, v181, v0
	v_add_f32_e32 v0, v197, v0
	v_mfma_f32_32x32x16_bf16 v[18:33], v[182:185], v[224:227], v[18:33]
	v_add_f32_e32 v0, v214, v0
	v_add_f32_e32 v0, v244, v0
	v_mfma_f32_32x32x16_bf16 v[34:49], v[198:201], v[220:223], v[34:49]
	v_add_f32_e32 v0, v245, v0
	v_add_f32_e32 v0, v246, v0
	v_mfma_f32_32x32x16_bf16 v[34:49], v[202:205], v[224:227], v[34:49]
	v_add_f32_e32 v0, v247, v0
	v_add_f32_e32 v0, v248, v0
	v_mfma_f32_32x32x16_bf16 v[66:81], v[206:209], v[220:223], v[66:81]
	v_add_f32_e32 v0, v228, v0
	v_add_f32_e32 v0, v229, v0
	v_mfma_f32_32x32x16_bf16 v[66:81], v[210:213], v[224:227], v[66:81]
	v_add_f32_e32 v0, v230, v0
	v_add_f32_e32 v0, v231, v0
	v_mfma_f32_32x32x16_bf16 v[50:65], v[236:239], v[220:223], v[50:65]
	v_add_f32_e32 v0, v232, v0
	v_add_f32_e32 v0, v233, v0
	v_mfma_f32_32x32x16_bf16 v[50:65], v[240:243], v[224:227], v[50:65]
	v_add_f32_e32 v0, v234, v0
	v_add_f32_e32 v0, v235, v0
	s_branch .LBB0_351
